# v84 + the five attention-loop vmcnt(0) skip branches inverted so the common path falls through
# baseline (speedup 1.0000x reference)
.LBB0_921:
	s_cmp_ge_i32 s13, s2
	s_cbranch_scc1 .LBB0_936
	s_waitcnt vmcnt(2)
	s_cmp_eq_u64 s[48:49], 0
	s_cbranch_scc0 .Lmoba_odd_rare

.Lmoba_odd_rare:
	s_waitcnt vmcnt(0)
	s_branch .Lmoba_odd_ok

.LBB0_1013:
	v_add_u32_e32 v212, v156, v157
	v_add_u32_e32 v213, v158, v157
	s_waitcnt vmcnt(2)
	s_add_i32 s98, s2, -3
	s_cmp_lt_i32 s98, s93
	s_cbranch_scc0 .Lsel_even_rare

.LBB0_1023:
	s_cmp_ge_i32 s13, s93
	s_cbranch_scc1 .LBB0_1012
	s_waitcnt vmcnt(2)
	s_cmp_le_i32 s3, s93
	s_cbranch_scc0 .Lsel_odd_rare

.LBB0_1037:
	s_waitcnt vmcnt(2)
	s_cmp_lt_i32 s13, s1
	s_cbranch_scc0 .Lwin_even_rare

.LBB0_1109:
	s_cmp_ge_i32 s13, s1
	s_cbranch_scc1 .LBB0_1182
	s_waitcnt vmcnt(2)
	s_cmp_eq_u64 s[94:95], 0
	s_cbranch_scc0 .Lwin_odd_rare
